# XCD-local rendezvous for the GEMM-to-GEMM seams (out->gate/up->down->in-proj), guarded by a start-up placement census; falls back to the two-level grid barrier
# speedup vs baseline: 1.0642x; 1.0106x over previous
_Z10fwd_kernel6Params:
	s_load_dwordx8 s[60:67], s[0:1], 0xa0
	s_load_dwordx8 s[12:19], s[0:1], 0x80
	s_load_dword s3, s[0:1], 0xc0
	s_add_u32 s4, s0, 0xb8
	s_addc_u32 s5, s1, 0
	v_and_b32_e32 v181, 0x3ff, v0
	v_cmp_gt_u32_e32 vcc, 2, v181
	s_waitcnt lgkmcnt(0)
	v_writelane_b32 v247, s3, 0
	v_writelane_b32 v247, s4, 1
	s_nop 1
	v_writelane_b32 v247, s5, 2
	s_and_saveexec_b64 s[4:5], vcc
	v_lshl_add_u32 v1, v181, 2, 0
	v_add_u32_e32 v1, 0x23fc0, v1
	v_mov_b32_e32 v2, 0
	ds_write_b32 v1, v2
	s_or_b64 exec, exec, s[4:5]
	s_load_dwordx16 s[44:59], s[0:1], 0x0
	s_load_dwordx16 s[68:83], s[0:1], 0x40
	s_add_u32 s0, s64, 0x80000
	s_addc_u32 s1, s65, 0
	s_waitcnt lgkmcnt(0)
	s_barrier
	v_writelane_b32 v247, s68, 3
	v_cmp_eq_u32_e64 s[4:5], 0, v181
	s_nop 0
	v_writelane_b32 v247, s69, 4
	v_writelane_b32 v247, s70, 5
	v_writelane_b32 v247, s71, 6
	v_writelane_b32 v247, s72, 7
	v_writelane_b32 v247, s73, 8
	v_writelane_b32 v247, s74, 9
	v_writelane_b32 v247, s75, 10
	v_writelane_b32 v247, s76, 11
	v_writelane_b32 v247, s77, 12
	v_writelane_b32 v247, s78, 13
	v_writelane_b32 v247, s79, 14
	v_writelane_b32 v247, s80, 15
	v_writelane_b32 v247, s81, 16
	v_writelane_b32 v247, s82, 17
	v_writelane_b32 v247, s83, 18
	v_writelane_b32 v247, s0, 19
	s_nop 1
	v_writelane_b32 v247, s1, 20
	s_getreg_b32 s0, hwreg(HW_REG_XCC_ID, 0, 4)
	s_and_b32 s0, s0, 15
	v_writelane_b32 v247, s0, 21
	s_mov_b64 s[0:1], exec
	v_writelane_b32 v247, s4, 22
	s_nop 1
	v_writelane_b32 v247, s5, 23
	s_and_b64 s[4:5], s[0:1], s[4:5]
	s_mov_b64 exec, s[4:5]
	s_cbranch_execz .LBB0_5
	s_mov_b64 s[4:5], exec
	v_mbcnt_lo_u32_b32 v1, s4, 0
	v_mbcnt_hi_u32_b32 v1, s5, v1
	v_cmp_eq_u32_e32 vcc, 0, v1
	s_and_b64 s[6:7], exec, vcc
	s_mov_b64 exec, s[6:7]
	s_cbranch_execz .LBB0_5
	v_readlane_b32 s3, v247, 21
	s_bcnt1_i32_b64 s4, s[4:5]
	s_lshl_b32 s3, s3, 8
	v_mov_b32_e32 v2, s4
	v_readlane_b32 s4, v247, 19
	v_mov_b32_e32 v1, s3
	v_readlane_b32 s5, v247, 20
	s_nop 4
	global_atomic_add v1, v2, s[4:5] offset:1024
	s_and_b32 s98, s2, 7
	s_lshl_b32 s98, s98, 2
	s_add_i32 s98, s98, 0x3600
	v_readlane_b32 s99, v247, 21
	v_mov_b32_e32 v1, s98
	s_lshl_b32 s99, 1, s99
	v_mov_b32_e32 v2, s99
	global_atomic_or v1, v2, s[4:5]

.LBB0_137:
	s_add_u32 s98, s64, 0x83600
	s_addc_u32 s99, s65, 0
	v_mov_b32_e32 v8, 0
	global_load_dwordx4 v[0:3], v8, s[98:99] sc1
	global_load_dwordx4 v[4:7], v8, s[98:99] offset:16 sc1
	s_waitcnt vmcnt(0)
	v_bcnt_u32_b32 v8, v0, v8
	v_bcnt_u32_b32 v8, v1, v8
	v_bcnt_u32_b32 v8, v2, v8
	v_bcnt_u32_b32 v8, v3, v8
	v_bcnt_u32_b32 v8, v4, v8
	v_bcnt_u32_b32 v8, v5, v8
	v_bcnt_u32_b32 v8, v6, v8
	v_bcnt_u32_b32 v8, v7, v8
	s_nop 1
	v_readfirstlane_b32 s98, v8
	s_nop 3
	s_cmp_eq_u32 s98, 8
	s_cselect_b32 s101, 1, 0
	s_cmp_eq_u32 s66, 0x100
	s_cselect_b32 s101, s101, 0
	v_mov_b32_e32 v0, v181
	s_add_u32 s68, s64, 0x200000
	v_and_b32_e32 v2, 0xff, v0
	v_ashrrev_i32_e32 v4, 8, v0
	v_lshlrev_b32_e32 v0, 2, v2
	v_lshl_or_b32 v0, v4, 10, v0
	s_addc_u32 s69, s65, 0
	s_ashr_i32 s3, s2, 31
	v_add_u32_e32 v0, 0, v0
	v_add_u32_e32 v3, 0x20000, v0
	v_mov_b64_e32 v[0:1], s[2:3]
	s_ashr_i32 s73, s66, 31
	s_mov_b32 s72, s66
	v_mad_i64_i32 v[0:1], s[0:1], s66, v4, v[0:1]
	s_lshl_b64 s[0:1], s[72:73], 1
	s_nop 0
	v_writelane_b32 v247, s0, 28
	s_mov_b64 s[4:5], 0x380
	s_mov_b32 s10, 0x92492493
	v_writelane_b32 v247, s1, 29
	s_mov_b64 s[0:1], 0
	v_mov_b32_e32 v4, 0x358637bd
	v_mov_b32_e32 v5, 0x70
	v_mov_b32_e32 v6, 0x71
	s_branch .LBB0_139

.Lcv_done:
.LBB0_546:
	s_waitcnt vmcnt(0)
	s_barrier
	s_mov_b64 s[0:1], exec
	v_readlane_b32 s4, v247, 22
	v_readlane_b32 s5, v247, 23
	s_and_b64 s[4:5], s[0:1], s[4:5]
	s_mov_b64 exec, s[4:5]
	s_cbranch_execz .LBB0_598
	s_add_i32 s4, 0, 0x23fc0
	s_waitcnt vmcnt(0)
	v_mov_b32_e32 v0, s4
	s_waitcnt vmcnt(0) expcnt(0) lgkmcnt(0)
	ds_read_b32 v2, v0
	s_add_i32 s4, 0, 0x23fc4
	v_mov_b32_e32 v0, s4
	ds_read_b32 v0, v0
	s_waitcnt lgkmcnt(1)
	v_cmp_ne_u32_e32 vcc, 0, v2
	s_cbranch_vccnz .LBB0_562
	v_readlane_b32 s4, v247, 1
	v_readlane_b32 s5, v247, 2
	s_load_dword s4, s[4:5], 0x14
	s_mov_b32 s33, 1
	v_mov_b32_e32 v16, 0
	s_waitcnt lgkmcnt(0)
	s_lshr_b32 s6, s4, 16
	s_and_b32 s4, s4, 0xffff
	s_cmp_lg_u32 s4, 0
	s_cselect_b64 s[4:5], -1, 0
	s_cmp_lg_u64 s[4:5], 0
	s_addc_u32 s4, s67, 0
	s_cmp_lg_u32 s6, 0
	s_mul_i32 s50, s4, s66
	s_cselect_b64 s[4:5], -1, 0
	s_cmp_lg_u64 s[4:5], 0
	v_readlane_b32 s4, v247, 0
	s_addc_u32 s4, s4, 0
	s_mul_i32 s50, s50, s4
	s_add_u32 s4, s64, 0x80200
	s_addc_u32 s5, s65, 0
	s_add_u32 s6, s64, 0x80400
	s_addc_u32 s7, s65, 0
	s_add_u32 s8, s64, 0x80500
	s_addc_u32 s9, s65, 0
	s_add_u32 s10, s64, 0x80600
	s_addc_u32 s11, s65, 0
	s_add_u32 s12, s64, 0x80700
	s_addc_u32 s13, s65, 0
	s_add_u32 s14, s64, 0x80800
	s_addc_u32 s15, s65, 0
	s_add_u32 s16, s64, 0x80900
	s_addc_u32 s17, s65, 0
	s_add_u32 s18, s64, 0x80a00
	s_addc_u32 s19, s65, 0
	s_add_u32 s20, s64, 0x80b00
	s_addc_u32 s21, s65, 0
	s_add_u32 s22, s64, 0x80c00
	s_addc_u32 s23, s65, 0
	s_add_u32 s24, s64, 0x80d00
	s_addc_u32 s25, s65, 0
	s_add_u32 s26, s64, 0x80e00
	s_addc_u32 s27, s65, 0
	s_add_u32 s28, s64, 0x80f00
	s_addc_u32 s29, s65, 0
	s_add_u32 s30, s64, 0x81000
	s_addc_u32 s31, s65, 0
	s_add_u32 s34, s64, 0x81100
	s_addc_u32 s35, s65, 0
	s_add_u32 s36, s64, 0x81200
	s_addc_u32 s37, s65, 0
	s_add_u32 s38, s64, 0x81300
	s_addc_u32 s39, s65, 0
	s_branch .LBB0_550

.LBB0_640:
	s_waitcnt vmcnt(0)
	s_waitcnt lgkmcnt(0)
	s_barrier
	s_mov_b64 s[0:1], exec
	v_readlane_b32 s4, v247, 22
	v_readlane_b32 s5, v247, 23
	s_and_b64 s[4:5], s[0:1], s[4:5]
	s_mov_b64 exec, s[4:5]
	s_cbranch_execz .LBB0_692
	s_cmp_lg_u32 s101, 0
	s_cbranch_scc0 .Lxl_orig_0
	s_and_b32 s4, s2, 7
	s_lshl_b32 s4, s4, 8
	s_add_i32 s4, s4, 0x83800
	s_add_u32 s98, s64, s4
	s_addc_u32 s99, s65, 0
	v_mov_b32_e32 v0, 0
	v_mov_b32_e32 v1, 1
	global_atomic_add v2, v0, v1, s[98:99] sc0
	s_mov_b32 s4, 0
	s_waitcnt vmcnt(0)
	v_readfirstlane_b32 s100, v2
	s_nop 3
	s_and_b32 s100, s100, 0xffffffe0
	s_add_i32 s100, s100, 32
.Lxl_spin_0:
	global_load_dword v2, v0, s[98:99] sc1
	s_add_i32 s4, s4, 1
	s_waitcnt vmcnt(0)
	v_readfirstlane_b32 s5, v2
	s_nop 3
	s_cmp_ge_u32 s5, s100
	s_cbranch_scc1 .Lxl_done_0
	s_cmp_gt_u32 s4, 0x40000
	s_cbranch_scc1 .Lxl_done_0
	s_sleep 1
	s_branch .Lxl_spin_0
.Lxl_done_0:
	buffer_inv sc1
	s_waitcnt vmcnt(0)
	s_branch .LBB0_692
.Lxl_orig_0:
	s_add_i32 s4, 0, 0x23fc0
	v_mov_b32_e32 v0, s4
	s_waitcnt vmcnt(0) expcnt(0) lgkmcnt(0)
	ds_read_b32 v2, v0
	s_add_i32 s4, 0, 0x23fc4
	v_mov_b32_e32 v0, s4
	ds_read_b32 v0, v0
	s_waitcnt lgkmcnt(1)
	v_cmp_ne_u32_e32 vcc, 0, v2
	s_cbranch_vccnz .LBB0_656
	v_readlane_b32 s4, v247, 1
	v_readlane_b32 s5, v247, 2
	s_load_dword s4, s[4:5], 0x14
	s_mov_b32 s33, 1
	v_mov_b32_e32 v16, 0
	s_waitcnt lgkmcnt(0)
	s_lshr_b32 s6, s4, 16
	s_and_b32 s4, s4, 0xffff
	s_cmp_lg_u32 s4, 0
	s_cselect_b64 s[4:5], -1, 0
	s_cmp_lg_u64 s[4:5], 0
	s_addc_u32 s4, s67, 0
	s_cmp_lg_u32 s6, 0
	s_mul_i32 s50, s4, s66
	s_cselect_b64 s[4:5], -1, 0
	s_cmp_lg_u64 s[4:5], 0
	v_readlane_b32 s4, v247, 0
	s_addc_u32 s4, s4, 0
	s_mul_i32 s50, s50, s4
	s_add_u32 s4, s64, 0x80200
	s_addc_u32 s5, s65, 0
	s_add_u32 s6, s64, 0x80400
	s_addc_u32 s7, s65, 0
	s_add_u32 s8, s64, 0x80500
	s_addc_u32 s9, s65, 0
	s_add_u32 s10, s64, 0x80600
	s_addc_u32 s11, s65, 0
	s_add_u32 s12, s64, 0x80700
	s_addc_u32 s13, s65, 0
	s_add_u32 s14, s64, 0x80800
	s_addc_u32 s15, s65, 0
	s_add_u32 s16, s64, 0x80900
	s_addc_u32 s17, s65, 0
	s_add_u32 s18, s64, 0x80a00
	s_addc_u32 s19, s65, 0
	s_add_u32 s20, s64, 0x80b00
	s_addc_u32 s21, s65, 0
	s_add_u32 s22, s64, 0x80c00
	s_addc_u32 s23, s65, 0
	s_add_u32 s24, s64, 0x80d00
	s_addc_u32 s25, s65, 0
	s_add_u32 s26, s64, 0x80e00
	s_addc_u32 s27, s65, 0
	s_add_u32 s28, s64, 0x80f00
	s_addc_u32 s29, s65, 0
	s_add_u32 s30, s64, 0x81000
	s_addc_u32 s31, s65, 0
	s_add_u32 s34, s64, 0x81100
	s_addc_u32 s35, s65, 0
	s_add_u32 s36, s64, 0x81200
	s_addc_u32 s37, s65, 0
	s_add_u32 s38, s64, 0x81300
	s_addc_u32 s39, s65, 0
	s_branch .LBB0_644

.LBB0_712:
	s_waitcnt vmcnt(0)
	s_waitcnt vmcnt(0)
	s_barrier
	s_mov_b64 s[0:1], exec
	v_readlane_b32 s4, v247, 22
	v_readlane_b32 s5, v247, 23
	s_and_b64 s[4:5], s[0:1], s[4:5]
	s_mov_b64 exec, s[4:5]
	s_cbranch_execz .LBB0_764
	s_cmp_lg_u32 s101, 0
	s_cbranch_scc0 .Lxl_orig_1
	s_and_b32 s4, s2, 7
	s_lshl_b32 s4, s4, 8
	s_add_i32 s4, s4, 0x83800
	s_add_u32 s98, s64, s4
	s_addc_u32 s99, s65, 0
	v_mov_b32_e32 v0, 0
	v_mov_b32_e32 v1, 1
	global_atomic_add v2, v0, v1, s[98:99] sc0
	s_mov_b32 s4, 0
	s_waitcnt vmcnt(0)
	v_readfirstlane_b32 s100, v2
	s_nop 3
	s_and_b32 s100, s100, 0xffffffe0
	s_add_i32 s100, s100, 32

.Lxl_orig_2:
	s_add_i32 s4, 0, 0x23fc0
	v_mov_b32_e32 v0, s4
	s_waitcnt vmcnt(0) expcnt(0) lgkmcnt(0)
	ds_read_b32 v2, v0
	s_add_i32 s4, 0, 0x23fc4
	v_mov_b32_e32 v0, s4
	ds_read_b32 v0, v0
	s_waitcnt lgkmcnt(1)
	v_cmp_ne_u32_e32 vcc, 0, v2
	s_cbranch_vccnz .LBB0_826
	v_readlane_b32 s4, v247, 0
	s_mul_i32 s33, s67, s4
	s_add_u32 s4, s64, 0x80200
	s_addc_u32 s5, s65, 0
	s_add_u32 s6, s64, 0x80400
	s_addc_u32 s7, s65, 0
	s_add_u32 s8, s64, 0x80500
	s_addc_u32 s9, s65, 0
	s_add_u32 s10, s64, 0x80600
	s_addc_u32 s11, s65, 0
	s_add_u32 s12, s64, 0x80700
	s_addc_u32 s13, s65, 0
	s_add_u32 s14, s64, 0x80800
	s_addc_u32 s15, s65, 0
	s_add_u32 s16, s64, 0x80900
	s_addc_u32 s17, s65, 0
	s_add_u32 s18, s64, 0x80a00
	s_addc_u32 s19, s65, 0
	s_add_u32 s20, s64, 0x80b00
	s_addc_u32 s21, s65, 0
	s_add_u32 s22, s64, 0x80c00
	s_addc_u32 s23, s65, 0
	s_add_u32 s24, s64, 0x80d00
	s_addc_u32 s25, s65, 0
	s_add_u32 s26, s64, 0x80e00
	s_addc_u32 s27, s65, 0
	s_add_u32 s28, s64, 0x80f00
	s_addc_u32 s29, s65, 0
	s_add_u32 s30, s64, 0x81000
	s_addc_u32 s31, s65, 0
	s_add_u32 s34, s64, 0x81100
	s_addc_u32 s35, s65, 0
	s_add_u32 s36, s64, 0x81200
	s_addc_u32 s37, s65, 0
	s_add_u32 s38, s64, 0x81300
	s_mul_i32 s33, s33, s66
	s_addc_u32 s39, s65, 0
	s_mov_b32 s50, 1
	v_mov_b32_e32 v16, 0
	s_branch .LBB0_814

.Lxl_orig_3:
	s_add_i32 s4, 0, 0x23fc0
	v_mov_b32_e32 v0, s4
	s_waitcnt vmcnt(0) expcnt(0) lgkmcnt(0)
	ds_read_b32 v2, v0
	s_add_i32 s4, 0, 0x23fc4
	v_mov_b32_e32 v0, s4
	ds_read_b32 v0, v0
	s_waitcnt lgkmcnt(1)
	v_cmp_ne_u32_e32 vcc, 0, v2
	s_cbranch_vccnz .LBB0_1330
	v_readlane_b32 s4, v247, 1
	v_readlane_b32 s5, v247, 2
	s_load_dword s4, s[4:5], 0x14
	s_mov_b32 s33, 1
	v_mov_b32_e32 v16, 0
	s_waitcnt lgkmcnt(0)
	s_lshr_b32 s6, s4, 16
	s_and_b32 s4, s4, 0xffff
	s_cmp_lg_u32 s4, 0
	s_cselect_b64 s[4:5], -1, 0
	s_cmp_lg_u64 s[4:5], 0
	s_addc_u32 s4, s67, 0
	s_cmp_lg_u32 s6, 0
	s_mul_i32 s46, s4, s66
	s_cselect_b64 s[4:5], -1, 0
	s_cmp_lg_u64 s[4:5], 0
	v_readlane_b32 s4, v247, 0
	s_addc_u32 s4, s4, 0
	s_mul_i32 s46, s46, s4
	s_add_u32 s4, s64, 0x80200
	s_addc_u32 s5, s65, 0
	s_add_u32 s6, s64, 0x80400
	s_addc_u32 s7, s65, 0
	s_add_u32 s8, s64, 0x80500
	s_addc_u32 s9, s65, 0
	s_add_u32 s10, s64, 0x80600
	s_addc_u32 s11, s65, 0
	s_add_u32 s12, s64, 0x80700
	s_addc_u32 s13, s65, 0
	s_add_u32 s14, s64, 0x80800
	s_addc_u32 s15, s65, 0
	s_add_u32 s16, s64, 0x80900
	s_addc_u32 s17, s65, 0
	s_add_u32 s18, s64, 0x80a00
	s_addc_u32 s19, s65, 0
	s_add_u32 s20, s64, 0x80b00
	s_addc_u32 s21, s65, 0
	s_add_u32 s22, s64, 0x80c00
	s_addc_u32 s23, s65, 0
	s_add_u32 s24, s64, 0x80d00
	s_addc_u32 s25, s65, 0
	s_add_u32 s26, s64, 0x80e00
	s_addc_u32 s27, s65, 0
	s_add_u32 s28, s64, 0x80f00
	s_addc_u32 s29, s65, 0
	s_add_u32 s30, s64, 0x81000
	s_addc_u32 s31, s65, 0
	s_add_u32 s34, s64, 0x81100
	s_addc_u32 s35, s65, 0
	s_add_u32 s36, s64, 0x81200
	s_addc_u32 s37, s65, 0
	s_add_u32 s38, s64, 0x81300
	s_addc_u32 s39, s65, 0
	s_branch .LBB0_1318
